# mLSTM prefetch un-serialized (v23 rename, vmcnt(2) at commit) + 4-group XCD stagger at P1 start to de-sync epilogue store bursts
# speedup vs baseline: 1.0044x; 1.0044x over previous
; #define LAS __attribute__((address_space(3)))
; __device__ __forceinline__ unsigned xb_add(unsigned* p, unsigned v) { return __hip_atomic_fetch_add(p, v, __ATOMIC_RELAXED, __HIP_MEMORY_SCOPE_AGENT); }
; __device__ __forceinline__ unsigned xb_xcc_id() { return (unsigned)__builtin_amdgcn_s_getreg((3 << 11) | 20) & 0xFu; }
; __device__ __forceinline__ XcdBarrier xcd_barrier_post(unsigned* bar, volatile LAS unsigned* st) {
;     XcdBarrier b; b.bar = bar; b.x = xb_xcc_id(); b.st = st;
;     if (threadIdx.x == 0) (void)xb_add(&bar[XB_XCNT(b.x)], 1u);
;     return b;
; }
.LBB0_109:
	s_getreg_b32 s0, hwreg(HW_REG_XCC_ID, 0, 4)
	s_and_b32 s0, s0, 15
	v_writelane_b32 v252, s0, 10
	s_and_b32 s1, s0, 3
.Lstag1_loop:
	s_cmp_eq_u32 s1, 0
	s_cbranch_scc1 .Lstag1_done
	s_sleep 127
	s_sub_u32 s1, s1, 1
	s_branch .Lstag1_loop
.Lstag1_done:
	v_cmp_eq_u32_e64 s[0:1], 0, v251
	s_mov_b64 s[2:3], exec
	s_nop 0
	v_writelane_b32 v252, s0, 11
	s_nop 1
	v_writelane_b32 v252, s1, 12
	s_and_b64 s[0:1], s[2:3], s[0:1]
	s_mov_b64 exec, s[0:1]
	s_cbranch_execz .LBB0_112
	s_mov_b64 s[4:5], exec
	v_mbcnt_lo_u32_b32 v0, s4, 0
	v_mbcnt_hi_u32_b32 v0, s5, v0
	v_cmp_eq_u32_e32 vcc, 0, v0
	s_and_b64 s[0:1], exec, vcc
	s_mov_b64 exec, s[0:1]
	s_cbranch_execz .LBB0_112
	v_readlane_b32 s0, v252, 10
	s_lshl_b32 s0, s0, 8
	s_bcnt1_i32_b64 s1, s[4:5]
	v_mov_b32_e32 v0, s0
	v_mov_b32_e32 v1, s1
	v_readlane_b32 s0, v252, 2
	v_readlane_b32 s1, v252, 3
	s_nop 4
	global_atomic_add v0, v1, s[0:1] offset:1024
